# attention prompt units: static s_setprio 1 for waves 4-7 (younger half), reset after the units
# baseline (speedup 1.0000x reference)
; __global__ void __launch_bounds__(512, 2) hybrid_fwd(Params P) {
;     ...
;                     attn_build_bias(Q, lds, li, (wg >> 1) & 15, tid);
;                     for (int u = wg * 8; u < wg * 8 + 8; ++u) attn_prompt_unit(Q, lds, li, u >> 8, (u >> 4) & 15, u & 15, tid);
.LBB0_67:
	s_cmp_lt_u32 s61, 4
	s_cbranch_scc1 .Lattn_prio0
	s_setprio 1

; #define LAS __attribute__((address_space(3)))
; __device__ __forceinline__ void attn_sample_unit(const Params& P, LAS unsigned char* lds, int li, int b, int h, const int tid) {
;     const int lane = tid & 63, wid = tid >> 6;
;     const bf16_t* QKV = (const bf16_t*)(P.ws + WS_R1); bf16_t* MIX = (bf16_t*)(P.ws + WS_MIX);
;     LAS float* qs = (LAS float*)lds;
;     LAS float* sc = qs + 1024;
;     LAS float* tab = sc + 16 * 528;
;     const size_t rb = (size_t)TP + b * SSEQ;
;     for (int i = tid; i < 1024; i += 512) qs[i] = bf2f(QKV[(rb + (i >> 6)) * NQKV + h * 64 + (i & 63)]);
;     if (tid < 257) tab[tid] = P.in[19][(size_t)(li * 16 + h) * 257 + tid];
; __global__ void __launch_bounds__(512, 2) hybrid_fwd(Params P) {
;     ...
;                     for (int u = wg * 8; u < wg * 8 + 8; ++u) attn_prompt_unit(Q, lds, li, u >> 8, (u >> 4) & 15, u & 15, tid);
;                     if (wg < 128) attn_sample_unit(Q, lds, li, wg >> 4, wg & 15, tid);
.LBB0_87:
	s_setprio 0
	v_readlane_b32 s22, v245, 51
	s_cmpk_lt_i32 s94, 0x80
	v_readlane_b32 s23, v245, 52
	s_cbranch_scc0 .LBB0_122
	s_and_b32 s2, s94, -16
	s_and_b32 s4, s94, 15
	s_ashr_i32 s0, s2, 31
	s_add_u32 s18, s2, 0x8000
	s_addc_u32 s19, s0, 0
	s_movk_i32 s0, 0x400
	v_cmp_gt_i32_e32 vcc, s0, v166
	s_and_saveexec_b64 s[0:1], vcc
	s_movk_i32 s14, 0x1ff
	s_cbranch_execz .LBB0_100
	s_lshl_b32 s12, s4, 7
	v_max_i32_e32 v2, 0x200, v166
	s_add_u32 s12, s64, s12
	v_sub_u32_e32 v2, v2, v166
	s_addc_u32 s13, s65, 0
	v_lshlrev_b32_e32 v160, 1, v164
	v_add_u32_e32 v3, 0x1ff, v2
	v_lshl_add_u64 v[0:1], s[12:13], 0, v[160:161]
	v_cmp_lt_u32_e32 vcc, s14, v3
	s_mov_b64 s[34:35], -1
	v_mov_b32_e32 v2, v166
	s_and_saveexec_b64 s[28:29], vcc
	s_cbranch_execz .LBB0_97
	v_lshrrev_b32_e32 v4, 9, v3
	v_add_u32_e32 v167, 0x200, v166
	v_add_u32_e32 v5, -1, v4
	v_cmp_lt_u32_e32 vcc, 1, v5
	v_mov_b32_e32 v6, 0
	v_mov_b64_e32 v[2:3], v[166:167]
	s_and_saveexec_b64 s[34:35], vcc
	s_cbranch_execz .LBB0_94
	v_lshrrev_b32_e32 v2, 1, v5
	v_add_u32_e32 v2, 1, v2
	v_and_b32_e32 v6, -2, v2
	v_lshl_add_u32 v7, v166, 2, 0
	s_mov_b32 s12, 0
	s_mov_b64 s[38:39], 0
	v_mov_b64_e32 v[2:3], v[166:167]
